# e8 + LRU loop: sink early conv-input copies/waits past next-block load latency
# speedup vs baseline: 1.0119x; 1.0098x over previous
.LBB0_222:
	s_mov_b32 s4, 0x3fb8aa3b
	v_pk_fma_f32 v[6:7], v[100:101], s[4:5], v[108:109] op_sel_hi:[1,0,1] neg_lo:[1,0,0] neg_hi:[1,0,0]
	s_mov_b32 s6, 0x3fb17218
	v_exp_f32_e32 v6, v6
	v_exp_f32_e32 v7, v7
	s_mov_b32 s0, 0x3d2aaaab
	s_mov_b32 s8, 0x3e2aaaab
	v_pk_fma_f32 v[8:9], v[96:97], s[4:5], v[110:111] op_sel_hi:[1,0,1] neg_lo:[1,0,0] neg_hi:[1,0,0]
	v_pk_add_f32 v[6:7], v[6:7], 1.0 op_sel_hi:[1,0]
	v_exp_f32_e32 v8, v8
	v_rcp_f32_e32 v6, v6
	v_rcp_f32_e32 v7, v7
	v_exp_f32_e32 v9, v9
	s_add_i32 s2, s2, 16
	v_pk_mul_f32 v[6:7], v[114:115], v[6:7]
	v_pk_add_f32 v[8:9], v[8:9], 1.0 op_sel_hi:[1,0]
	v_exp_f32_e32 v100, v6
	v_exp_f32_e32 v101, v7
	v_pk_mul_f32 v[10:11], v[6:7], s[6:7] op_sel_hi:[1,0]
	v_mov_b64_e32 v[6:7], s[0:1]
	s_mov_b32 s0, 0x3c088889
	v_pk_fma_f32 v[12:13], v[10:11], s[0:1], v[6:7] op_sel_hi:[1,0,0]
	v_pk_fma_f32 v[14:15], v[100:101], v[100:101], 1.0 op_sel_hi:[1,1,0] neg_lo:[1,0,0] neg_hi:[1,0,0]
	v_pk_fma_f32 v[12:13], v[10:11], v[12:13], s[8:9] op_sel_hi:[1,1,0]
	v_cmp_lt_f32_e32 vcc, s7, v10
	v_pk_fma_f32 v[12:13], v[10:11], v[12:13], 0.5 op_sel_hi:[1,1,0]
	v_rcp_f32_e32 v8, v8
	v_pk_fma_f32 v[12:13], v[10:11], v[12:13], 1.0 op_sel_hi:[1,1,0]
	v_rcp_f32_e32 v9, v9
	v_pk_mul_f32 v[12:13], v[10:11], v[12:13] neg_lo:[0,1] neg_hi:[0,1]
	v_cndmask_b32_e32 v10, v14, v12, vcc
	v_cmp_lt_f32_e32 vcc, s7, v11
	v_pk_mul_f32 v[4:5], v[4:5], v[8:9]
	v_pk_fma_f32 v[8:9], v[92:93], s[4:5], v[122:123] op_sel_hi:[1,0,1] neg_lo:[1,0,0] neg_hi:[1,0,0]
	v_cndmask_b32_e32 v11, v15, v13, vcc
	v_pk_fma_f32 v[12:13], v[102:103], s[4:5], v[116:117] op_sel_hi:[1,0,1] neg_lo:[1,0,0] neg_hi:[1,0,0]
	v_pk_fma_f32 v[14:15], v[98:99], s[4:5], v[118:119] op_sel_hi:[1,0,1] neg_lo:[1,0,0] neg_hi:[1,0,0]
	v_exp_f32_e32 v12, v12
	v_exp_f32_e32 v13, v13
	v_exp_f32_e32 v8, v8
	v_exp_f32_e32 v9, v9
	v_exp_f32_e32 v14, v14
	v_pk_add_f32 v[12:13], v[12:13], 1.0 op_sel_hi:[1,0]
	v_exp_f32_e32 v15, v15
	v_rcp_f32_e32 v12, v12
	v_rcp_f32_e32 v13, v13
	v_pk_add_f32 v[8:9], v[8:9], 1.0 op_sel_hi:[1,0]
	v_pk_add_f32 v[14:15], v[14:15], 1.0 op_sel_hi:[1,0]
	v_rcp_f32_e32 v8, v8
	v_pk_mul_f32 v[12:13], v[120:121], v[12:13]
	v_rcp_f32_e32 v9, v9
	v_exp_f32_e32 v96, v12
	v_exp_f32_e32 v97, v13
	v_pk_mul_f32 v[12:13], v[12:13], s[6:7] op_sel_hi:[1,0]
	v_sqrt_f32_e32 v10, v10
	v_pk_fma_f32 v[16:17], v[12:13], s[0:1], v[6:7] op_sel_hi:[1,0,0]
	v_pk_fma_f32 v[18:19], v[96:97], v[96:97], 1.0 op_sel_hi:[1,1,0] neg_lo:[1,0,0] neg_hi:[1,0,0]
	v_pk_fma_f32 v[16:17], v[12:13], v[16:17], s[8:9] op_sel_hi:[1,1,0]
	v_cmp_lt_f32_e32 vcc, s7, v12
	v_pk_fma_f32 v[16:17], v[12:13], v[16:17], 0.5 op_sel_hi:[1,1,0]
	v_sqrt_f32_e32 v11, v11
	v_pk_fma_f32 v[16:17], v[12:13], v[16:17], 1.0 op_sel_hi:[1,1,0]
	v_rcp_f32_e32 v14, v14
	v_pk_mul_f32 v[16:17], v[12:13], v[16:17] neg_lo:[0,1] neg_hi:[0,1]
	v_rcp_f32_e32 v15, v15
	v_cndmask_b32_e32 v12, v18, v16, vcc
	v_cmp_lt_f32_e32 vcc, s7, v13
	v_sqrt_f32_e32 v12, v12
	v_pk_mul_f32 v[8:9], v[126:127], v[8:9]
	v_cndmask_b32_e32 v13, v19, v17, vcc
	v_sqrt_f32_e32 v13, v13
	v_pk_mul_f32 v[102:103], v[4:5], v[10:11]
	v_pk_mul_f32 v[4:5], v[78:79], v[14:15]
	v_exp_f32_e32 v92, v8
	v_exp_f32_e32 v93, v9
	v_pk_mul_f32 v[8:9], v[8:9], s[6:7] op_sel_hi:[1,0]
	v_pk_mul_f32 v[172:173], v[4:5], v[12:13]
	v_pk_fma_f32 v[12:13], v[8:9], s[0:1], v[6:7] op_sel_hi:[1,0,0]
	v_pk_fma_f32 v[14:15], v[92:93], v[92:93], 1.0 op_sel_hi:[1,1,0] neg_lo:[1,0,0] neg_hi:[1,0,0]
	v_pk_fma_f32 v[12:13], v[8:9], v[12:13], s[8:9] op_sel_hi:[1,1,0]
	v_cmp_lt_f32_e32 vcc, s7, v8
	v_pk_fma_f32 v[12:13], v[8:9], v[12:13], 0.5 op_sel_hi:[1,1,0]
	v_mov_b32_e32 v78, v173
	v_pk_fma_f32 v[12:13], v[8:9], v[12:13], 1.0 op_sel_hi:[1,1,0]
	v_mov_b32_e32 v4, v101
	v_pk_mul_f32 v[12:13], v[8:9], v[12:13] neg_lo:[0,1] neg_hi:[0,1]
	v_mov_b32_e32 v5, v96
	v_cndmask_b32_e32 v8, v14, v12, vcc
	v_cmp_lt_f32_e32 vcc, s7, v9
	s_nop 1
v_fmac_f32_dpp v102, v239, v100 row_shl:15 row_mask:0xf bank_mask:0xf
 v_fmac_f32_dpp v103, v240, v4 row_shl:15 row_mask:0xf bank_mask:0xf
v_fmac_f32_dpp v172, v241, v5 row_shl:15 row_mask:0xf bank_mask:0xf
 v_fmac_f32_dpp v78, v242, v97 row_shl:15 row_mask:0xf bank_mask:0xf
v_mul_f32_dpp v100, v179, v100 row_shl:15 row_mask:0xf bank_mask:0xf
 v_mul_f32_dpp v4, v236, v4 row_shl:15 row_mask:0xf bank_mask:0xf
v_mul_f32_dpp v5, v237, v5 row_shl:15 row_mask:0xf bank_mask:0xf
 v_mul_f32_dpp v97, v238, v97 row_shl:15 row_mask:0xf bank_mask:0xf
v_fmac_f32_dpp v102, v102, v100 row_shr:1 row_mask:0xf bank_mask:0xf
 v_fmac_f32_dpp v103, v103, v4 row_shr:1 row_mask:0xf bank_mask:0xf
v_fmac_f32_dpp v172, v172, v5 row_shr:1 row_mask:0xf bank_mask:0xf
 v_fmac_f32_dpp v78, v78, v97 row_shr:1 row_mask:0xf bank_mask:0xf
v_mul_f32_dpp v100, v100, v100 row_shr:1 row_mask:0xf bank_mask:0xf
 v_mul_f32_dpp v4, v4, v4 row_shr:1 row_mask:0xf bank_mask:0xf
v_mul_f32_dpp v5, v5, v5 row_shr:1 row_mask:0xf bank_mask:0xf
 v_mul_f32_dpp v97, v97, v97 row_shr:1 row_mask:0xf bank_mask:0xf
v_fmac_f32_dpp v102, v102, v100 row_shr:2 row_mask:0xf bank_mask:0xf
 v_fmac_f32_dpp v103, v103, v4 row_shr:2 row_mask:0xf bank_mask:0xf
v_fmac_f32_dpp v172, v172, v5 row_shr:2 row_mask:0xf bank_mask:0xf
 v_fmac_f32_dpp v78, v78, v97 row_shr:2 row_mask:0xf bank_mask:0xf
v_mul_f32_dpp v100, v100, v100 row_shr:2 row_mask:0xf bank_mask:0xf
 v_mul_f32_dpp v4, v4, v4 row_shr:2 row_mask:0xf bank_mask:0xf
v_mul_f32_dpp v5, v5, v5 row_shr:2 row_mask:0xf bank_mask:0xf
 v_mul_f32_dpp v97, v97, v97 row_shr:2 row_mask:0xf bank_mask:0xf
v_fmac_f32_dpp v102, v102, v100 row_shr:4 row_mask:0xf bank_mask:0xf
 v_fmac_f32_dpp v103, v103, v4 row_shr:4 row_mask:0xf bank_mask:0xf
v_fmac_f32_dpp v172, v172, v5 row_shr:4 row_mask:0xf bank_mask:0xf
 v_fmac_f32_dpp v78, v78, v97 row_shr:4 row_mask:0xf bank_mask:0xf
v_mul_f32_dpp v100, v100, v100 row_shr:4 row_mask:0xf bank_mask:0xf
 v_mul_f32_dpp v4, v4, v4 row_shr:4 row_mask:0xf bank_mask:0xf
v_mul_f32_dpp v5, v5, v5 row_shr:4 row_mask:0xf bank_mask:0xf
 v_mul_f32_dpp v97, v97, v97 row_shr:4 row_mask:0xf bank_mask:0xf
v_fmac_f32_dpp v102, v102, v100 row_shr:8 row_mask:0xf bank_mask:0xf
 v_fmac_f32_dpp v103, v103, v4 row_shr:8 row_mask:0xf bank_mask:0xf
v_fmac_f32_dpp v172, v172, v5 row_shr:8 row_mask:0xf bank_mask:0xf
 v_fmac_f32_dpp v78, v78, v97 row_shr:8 row_mask:0xf bank_mask:0xf
v_mul_f32_dpp v100, v100, v100 row_shr:8 row_mask:0xf bank_mask:0xf
 v_mul_f32_dpp v4, v4, v4 row_shr:8 row_mask:0xf bank_mask:0xf
v_mul_f32_dpp v5, v5, v5 row_shr:8 row_mask:0xf bank_mask:0xf
 v_mul_f32_dpp v97, v97, v97 row_shr:8 row_mask:0xf bank_mask:0xf
s_nop 1

	v_pk_fma_f32 v[10:11], v[88:89], s[4:5], v[124:125] op_sel_hi:[1,0,1] neg_lo:[1,0,0] neg_hi:[1,0,0]
	v_sqrt_f32_e32 v8, v8
	v_cndmask_b32_e32 v9, v15, v13, vcc
	v_pk_fma_f32 v[12:13], v[94:95], s[4:5], v[128:129] op_sel_hi:[1,0,1] neg_lo:[1,0,0] neg_hi:[1,0,0]
	v_exp_f32_e32 v10, v10
	v_exp_f32_e32 v12, v12
	v_exp_f32_e32 v13, v13
	v_exp_f32_e32 v11, v11
	v_pk_fma_f32 v[14:15], v[90:91], s[4:5], v[130:131] op_sel_hi:[1,0,1] neg_lo:[1,0,0] neg_hi:[1,0,0]
	v_sqrt_f32_e32 v9, v9
	v_pk_add_f32 v[12:13], v[12:13], 1.0 op_sel_hi:[1,0]
	v_exp_f32_e32 v14, v14
	v_rcp_f32_e32 v12, v12
	v_rcp_f32_e32 v13, v13
	v_exp_f32_e32 v15, v15
	v_pk_add_f32 v[10:11], v[10:11], 1.0 op_sel_hi:[1,0]
	v_mov_b32_e32 v96, v93
	v_pk_mul_f32 v[12:13], v[132:133], v[12:13]
	v_rcp_f32_e32 v10, v10
	v_exp_f32_e32 v178, v12
	v_exp_f32_e32 v179, v13
	v_pk_mul_f32 v[12:13], v[12:13], s[6:7] op_sel_hi:[1,0]
	v_rcp_f32_e32 v11, v11
	v_pk_fma_f32 v[16:17], v[12:13], s[0:1], v[6:7] op_sel_hi:[1,0,0]
	v_pk_fma_f32 v[18:19], v[178:179], v[178:179], 1.0 op_sel_hi:[1,1,0] neg_lo:[1,0,0] neg_hi:[1,0,0]
	v_pk_fma_f32 v[16:17], v[12:13], v[16:17], s[8:9] op_sel_hi:[1,1,0]
	v_cmp_lt_f32_e32 vcc, s7, v12
	v_pk_fma_f32 v[16:17], v[12:13], v[16:17], 0.5 op_sel_hi:[1,1,0]
	v_pk_add_f32 v[14:15], v[14:15], 1.0 op_sel_hi:[1,0]
	v_pk_fma_f32 v[16:17], v[12:13], v[16:17], 1.0 op_sel_hi:[1,1,0]
	v_rcp_f32_e32 v14, v14
	v_pk_mul_f32 v[16:17], v[12:13], v[16:17] neg_lo:[0,1] neg_hi:[0,1]
	v_rcp_f32_e32 v15, v15
	v_cndmask_b32_e32 v12, v18, v16, vcc
	v_cmp_lt_f32_e32 vcc, s7, v13
	v_sqrt_f32_e32 v12, v12
	v_pk_mul_f32 v[10:11], v[174:175], v[10:11]
	v_cndmask_b32_e32 v13, v19, v17, vcc
	v_sqrt_f32_e32 v13, v13
	v_pk_mul_f32 v[98:99], v[10:11], v[8:9]
	v_pk_mul_f32 v[8:9], v[176:177], v[14:15]
	v_pk_fma_f32 v[10:11], v[80:81], s[4:5], v[136:137] op_sel_hi:[1,0,1] neg_lo:[1,0,0] neg_hi:[1,0,0]
	v_pk_mul_f32 v[174:175], v[8:9], v[12:13]
	v_pk_fma_f32 v[8:9], v[84:85], s[4:5], v[134:135] op_sel_hi:[1,0,1] neg_lo:[1,0,0] neg_hi:[1,0,0]
	v_exp_f32_e32 v10, v10
	v_exp_f32_e32 v8, v8
	v_exp_f32_e32 v9, v9
	v_exp_f32_e32 v11, v11
	v_mov_b32_e32 v94, v175
	v_mov_b32_e32 v79, v98
	v_pk_add_f32 v[8:9], v[8:9], 1.0 op_sel_hi:[1,0]
	v_pk_add_f32 v[10:11], v[10:11], 1.0 op_sel_hi:[1,0]
	v_rcp_f32_e32 v8, v8
	v_rcp_f32_e32 v9, v9
	v_rcp_f32_e32 v10, v10
	v_rcp_f32_e32 v11, v11
	v_mov_b32_e32 v98, v179
	v_pk_mul_f32 v[8:9], v[138:139], v[8:9]
	s_nop 1
v_fmac_f32_dpp v79, v232, v92 row_shl:15 row_mask:0xf bank_mask:0xf
 v_fmac_f32_dpp v99, v233, v96 row_shl:15 row_mask:0xf bank_mask:0xf
v_fmac_f32_dpp v174, v234, v178 row_shl:15 row_mask:0xf bank_mask:0xf
 v_fmac_f32_dpp v94, v235, v98 row_shl:15 row_mask:0xf bank_mask:0xf
v_mul_f32_dpp v92, v228, v92 row_shl:15 row_mask:0xf bank_mask:0xf
 v_mul_f32_dpp v96, v229, v96 row_shl:15 row_mask:0xf bank_mask:0xf
v_mul_f32_dpp v178, v230, v178 row_shl:15 row_mask:0xf bank_mask:0xf
 v_mul_f32_dpp v98, v231, v98 row_shl:15 row_mask:0xf bank_mask:0xf
v_fmac_f32_dpp v79, v79, v92 row_shr:1 row_mask:0xf bank_mask:0xf
 v_fmac_f32_dpp v99, v99, v96 row_shr:1 row_mask:0xf bank_mask:0xf
v_fmac_f32_dpp v174, v174, v178 row_shr:1 row_mask:0xf bank_mask:0xf
 v_fmac_f32_dpp v94, v94, v98 row_shr:1 row_mask:0xf bank_mask:0xf
v_mul_f32_dpp v92, v92, v92 row_shr:1 row_mask:0xf bank_mask:0xf
 v_mul_f32_dpp v96, v96, v96 row_shr:1 row_mask:0xf bank_mask:0xf
v_mul_f32_dpp v178, v178, v178 row_shr:1 row_mask:0xf bank_mask:0xf
 v_mul_f32_dpp v98, v98, v98 row_shr:1 row_mask:0xf bank_mask:0xf
v_fmac_f32_dpp v79, v79, v92 row_shr:2 row_mask:0xf bank_mask:0xf
 v_fmac_f32_dpp v99, v99, v96 row_shr:2 row_mask:0xf bank_mask:0xf
v_fmac_f32_dpp v174, v174, v178 row_shr:2 row_mask:0xf bank_mask:0xf
 v_fmac_f32_dpp v94, v94, v98 row_shr:2 row_mask:0xf bank_mask:0xf
v_mul_f32_dpp v92, v92, v92 row_shr:2 row_mask:0xf bank_mask:0xf
 v_mul_f32_dpp v96, v96, v96 row_shr:2 row_mask:0xf bank_mask:0xf
v_mul_f32_dpp v178, v178, v178 row_shr:2 row_mask:0xf bank_mask:0xf
 v_mul_f32_dpp v98, v98, v98 row_shr:2 row_mask:0xf bank_mask:0xf
v_fmac_f32_dpp v79, v79, v92 row_shr:4 row_mask:0xf bank_mask:0xf
 v_fmac_f32_dpp v99, v99, v96 row_shr:4 row_mask:0xf bank_mask:0xf
v_fmac_f32_dpp v174, v174, v178 row_shr:4 row_mask:0xf bank_mask:0xf
 v_fmac_f32_dpp v94, v94, v98 row_shr:4 row_mask:0xf bank_mask:0xf
v_mul_f32_dpp v92, v92, v92 row_shr:4 row_mask:0xf bank_mask:0xf
 v_mul_f32_dpp v96, v96, v96 row_shr:4 row_mask:0xf bank_mask:0xf
v_mul_f32_dpp v178, v178, v178 row_shr:4 row_mask:0xf bank_mask:0xf
 v_mul_f32_dpp v98, v98, v98 row_shr:4 row_mask:0xf bank_mask:0xf
v_fmac_f32_dpp v79, v79, v92 row_shr:8 row_mask:0xf bank_mask:0xf
 v_fmac_f32_dpp v99, v99, v96 row_shr:8 row_mask:0xf bank_mask:0xf
v_fmac_f32_dpp v174, v174, v178 row_shr:8 row_mask:0xf bank_mask:0xf
 v_fmac_f32_dpp v94, v94, v98 row_shr:8 row_mask:0xf bank_mask:0xf
v_mul_f32_dpp v92, v92, v92 row_shr:8 row_mask:0xf bank_mask:0xf
 v_mul_f32_dpp v96, v96, v96 row_shr:8 row_mask:0xf bank_mask:0xf
v_mul_f32_dpp v178, v178, v178 row_shr:8 row_mask:0xf bank_mask:0xf
 v_mul_f32_dpp v98, v98, v98 row_shr:8 row_mask:0xf bank_mask:0xf
s_nop 1

	v_pk_mul_f32 v[10:11], v[162:163], v[10:11]
	v_exp_f32_e32 v80, v8
	v_exp_f32_e32 v81, v9
	v_pk_mul_f32 v[8:9], v[8:9], s[6:7] op_sel_hi:[1,0]
	s_waitcnt vmcnt(0)
	v_mov_b64_e32 v[26:27], v[58:59]
	v_mov_b64_e32 v[30:31], v[66:67]
	v_mov_b64_e32 v[22:23], v[54:55]
	v_pk_fma_f32 v[12:13], v[8:9], s[0:1], v[6:7] op_sel_hi:[1,0,0]
	v_pk_fma_f32 v[14:15], v[80:81], v[80:81], 1.0 op_sel_hi:[1,1,0] neg_lo:[1,0,0] neg_hi:[1,0,0]
	v_pk_fma_f32 v[12:13], v[8:9], v[12:13], s[8:9] op_sel_hi:[1,1,0]
	v_cmp_lt_f32_e32 vcc, s7, v8
	v_pk_fma_f32 v[12:13], v[8:9], v[12:13], 0.5 op_sel_hi:[1,1,0]
	v_mov_b64_e32 v[34:35], v[62:63]
	v_pk_fma_f32 v[12:13], v[8:9], v[12:13], 1.0 op_sel_hi:[1,1,0]
	s_cmpk_eq_i32 s2, 0x80
	v_pk_mul_f32 v[12:13], v[8:9], v[12:13] neg_lo:[0,1] neg_hi:[0,1]
	v_mov_b32_e32 v179, v100
	v_cndmask_b32_e32 v8, v14, v12, vcc
	v_cmp_lt_f32_e32 vcc, s7, v9
	v_sqrt_f32_e32 v8, v8
	v_mov_b32_e32 v236, v4
	v_cndmask_b32_e32 v9, v15, v13, vcc
	v_pk_fma_f32 v[12:13], v[86:87], s[4:5], v[140:141] op_sel_hi:[1,0,1] neg_lo:[1,0,0] neg_hi:[1,0,0]
	v_pk_fma_f32 v[14:15], v[82:83], s[4:5], v[142:143] op_sel_hi:[1,0,1] neg_lo:[1,0,0] neg_hi:[1,0,0]
	v_exp_f32_e32 v12, v12
	v_exp_f32_e32 v13, v13
	v_exp_f32_e32 v14, v14
	v_exp_f32_e32 v15, v15
	v_sqrt_f32_e32 v9, v9
	v_pk_add_f32 v[12:13], v[12:13], 1.0 op_sel_hi:[1,0]
	v_mov_b32_e32 v237, v5
	v_rcp_f32_e32 v12, v12
	v_rcp_f32_e32 v13, v13
	v_pk_add_f32 v[14:15], v[14:15], 1.0 op_sel_hi:[1,0]
	v_pk_mul_f32 v[84:85], v[10:11], v[8:9]
	v_rcp_f32_e32 v14, v14
	v_pk_mul_f32 v[12:13], v[144:145], v[12:13]
	v_rcp_f32_e32 v15, v15
	v_exp_f32_e32 v82, v12
	v_exp_f32_e32 v83, v13
	v_pk_mul_f32 v[12:13], v[12:13], s[6:7] op_sel_hi:[1,0]
	v_pk_mul_f32 v[8:9], v[168:169], v[14:15]
	v_pk_fma_f32 v[16:17], v[12:13], s[0:1], v[6:7] op_sel_hi:[1,0,0]
	v_pk_fma_f32 v[18:19], v[82:83], v[82:83], 1.0 op_sel_hi:[1,1,0] neg_lo:[1,0,0] neg_hi:[1,0,0]
	v_pk_fma_f32 v[16:17], v[12:13], v[16:17], s[8:9] op_sel_hi:[1,1,0]
	v_cmp_lt_f32_e32 vcc, s7, v12
	v_pk_fma_f32 v[16:17], v[12:13], v[16:17], 0.5 op_sel_hi:[1,1,0]
	v_pk_fma_f32 v[10:11], v[70:71], s[4:5], v[148:149] op_sel_hi:[1,0,1] neg_lo:[1,0,0] neg_hi:[1,0,0]
	v_pk_fma_f32 v[16:17], v[12:13], v[16:17], 1.0 op_sel_hi:[1,1,0]
	v_exp_f32_e32 v10, v10
	v_pk_mul_f32 v[16:17], v[12:13], v[16:17] neg_lo:[0,1] neg_hi:[0,1]
	v_exp_f32_e32 v11, v11
	v_cndmask_b32_e32 v12, v18, v16, vcc
	v_cmp_lt_f32_e32 vcc, s7, v13
	v_sqrt_f32_e32 v12, v12
	v_pk_add_f32 v[10:11], v[10:11], 1.0 op_sel_hi:[1,0]
	v_cndmask_b32_e32 v13, v19, v17, vcc
	v_sqrt_f32_e32 v13, v13
	v_rcp_f32_e32 v10, v10
	v_rcp_f32_e32 v11, v11
	v_mov_b64_e32 v[18:19], v[46:47]
	v_pk_mul_f32 v[86:87], v[8:9], v[12:13]
	v_pk_fma_f32 v[8:9], v[74:75], s[4:5], v[146:147] op_sel_hi:[1,0,1] neg_lo:[1,0,0] neg_hi:[1,0,0]
	v_pk_mul_f32 v[10:11], v[158:159], v[10:11]
	v_exp_f32_e32 v8, v8
	v_exp_f32_e32 v9, v9
	s_nop 1
v_fmac_f32_dpp v84, v224, v80 row_shl:15 row_mask:0xf bank_mask:0xf
 v_fmac_f32_dpp v85, v225, v81 row_shl:15 row_mask:0xf bank_mask:0xf
v_fmac_f32_dpp v86, v226, v82 row_shl:15 row_mask:0xf bank_mask:0xf
 v_fmac_f32_dpp v87, v227, v83 row_shl:15 row_mask:0xf bank_mask:0xf
v_mul_f32_dpp v80, v220, v80 row_shl:15 row_mask:0xf bank_mask:0xf
 v_mul_f32_dpp v81, v221, v81 row_shl:15 row_mask:0xf bank_mask:0xf
v_mul_f32_dpp v82, v222, v82 row_shl:15 row_mask:0xf bank_mask:0xf
 v_mul_f32_dpp v83, v223, v83 row_shl:15 row_mask:0xf bank_mask:0xf
v_fmac_f32_dpp v84, v84, v80 row_shr:1 row_mask:0xf bank_mask:0xf
 v_fmac_f32_dpp v85, v85, v81 row_shr:1 row_mask:0xf bank_mask:0xf
v_fmac_f32_dpp v86, v86, v82 row_shr:1 row_mask:0xf bank_mask:0xf
 v_fmac_f32_dpp v87, v87, v83 row_shr:1 row_mask:0xf bank_mask:0xf
v_mul_f32_dpp v80, v80, v80 row_shr:1 row_mask:0xf bank_mask:0xf
 v_mul_f32_dpp v81, v81, v81 row_shr:1 row_mask:0xf bank_mask:0xf
v_mul_f32_dpp v82, v82, v82 row_shr:1 row_mask:0xf bank_mask:0xf
 v_mul_f32_dpp v83, v83, v83 row_shr:1 row_mask:0xf bank_mask:0xf
v_fmac_f32_dpp v84, v84, v80 row_shr:2 row_mask:0xf bank_mask:0xf
 v_fmac_f32_dpp v85, v85, v81 row_shr:2 row_mask:0xf bank_mask:0xf
v_fmac_f32_dpp v86, v86, v82 row_shr:2 row_mask:0xf bank_mask:0xf
 v_fmac_f32_dpp v87, v87, v83 row_shr:2 row_mask:0xf bank_mask:0xf
v_mul_f32_dpp v80, v80, v80 row_shr:2 row_mask:0xf bank_mask:0xf
 v_mul_f32_dpp v81, v81, v81 row_shr:2 row_mask:0xf bank_mask:0xf
v_mul_f32_dpp v82, v82, v82 row_shr:2 row_mask:0xf bank_mask:0xf
 v_mul_f32_dpp v83, v83, v83 row_shr:2 row_mask:0xf bank_mask:0xf
v_fmac_f32_dpp v84, v84, v80 row_shr:4 row_mask:0xf bank_mask:0xf
 v_fmac_f32_dpp v85, v85, v81 row_shr:4 row_mask:0xf bank_mask:0xf
v_fmac_f32_dpp v86, v86, v82 row_shr:4 row_mask:0xf bank_mask:0xf
 v_fmac_f32_dpp v87, v87, v83 row_shr:4 row_mask:0xf bank_mask:0xf
v_mul_f32_dpp v80, v80, v80 row_shr:4 row_mask:0xf bank_mask:0xf
 v_mul_f32_dpp v81, v81, v81 row_shr:4 row_mask:0xf bank_mask:0xf
v_mul_f32_dpp v82, v82, v82 row_shr:4 row_mask:0xf bank_mask:0xf
 v_mul_f32_dpp v83, v83, v83 row_shr:4 row_mask:0xf bank_mask:0xf
v_fmac_f32_dpp v84, v84, v80 row_shr:8 row_mask:0xf bank_mask:0xf
 v_fmac_f32_dpp v85, v85, v81 row_shr:8 row_mask:0xf bank_mask:0xf
v_fmac_f32_dpp v86, v86, v82 row_shr:8 row_mask:0xf bank_mask:0xf
 v_fmac_f32_dpp v87, v87, v83 row_shr:8 row_mask:0xf bank_mask:0xf
v_mul_f32_dpp v80, v80, v80 row_shr:8 row_mask:0xf bank_mask:0xf
 v_mul_f32_dpp v81, v81, v81 row_shr:8 row_mask:0xf bank_mask:0xf
v_mul_f32_dpp v82, v82, v82 row_shr:8 row_mask:0xf bank_mask:0xf
 v_mul_f32_dpp v83, v83, v83 row_shr:8 row_mask:0xf bank_mask:0xf
s_nop 1

	v_mov_b32_e32 v238, v97
	v_mov_b32_e32 v228, v92
	v_pk_add_f32 v[8:9], v[8:9], 1.0 op_sel_hi:[1,0]
	v_mov_b32_e32 v229, v96
	v_rcp_f32_e32 v8, v8
	v_rcp_f32_e32 v9, v9
	v_mov_b32_e32 v230, v178
	v_mov_b32_e32 v231, v98
	v_mov_b32_e32 v220, v80
	v_pk_mul_f32 v[8:9], v[150:151], v[8:9]
	v_mov_b32_e32 v221, v81
	v_exp_f32_e32 v70, v8
	v_exp_f32_e32 v71, v9
	v_pk_mul_f32 v[8:9], v[8:9], s[6:7] op_sel_hi:[1,0]
	v_mov_b32_e32 v222, v82
	v_pk_fma_f32 v[12:13], v[8:9], s[0:1], v[6:7] op_sel_hi:[1,0,0]
	v_pk_fma_f32 v[14:15], v[70:71], v[70:71], 1.0 op_sel_hi:[1,1,0] neg_lo:[1,0,0] neg_hi:[1,0,0]
	v_pk_fma_f32 v[12:13], v[8:9], v[12:13], s[8:9] op_sel_hi:[1,1,0]
	v_cmp_lt_f32_e32 vcc, s7, v8
	v_pk_fma_f32 v[12:13], v[8:9], v[12:13], 0.5 op_sel_hi:[1,1,0]
	v_mov_b32_e32 v223, v83
	v_pk_fma_f32 v[12:13], v[8:9], v[12:13], 1.0 op_sel_hi:[1,1,0]
	v_mov_b64_e32 v[28:29], v[60:61]
	v_pk_mul_f32 v[12:13], v[8:9], v[12:13] neg_lo:[0,1] neg_hi:[0,1]
	v_mov_b64_e32 v[32:33], v[68:69]
	v_cndmask_b32_e32 v8, v14, v12, vcc
	v_cmp_lt_f32_e32 vcc, s7, v9
	v_sqrt_f32_e32 v8, v8
	v_mov_b64_e32 v[20:21], v[48:49]
	v_cndmask_b32_e32 v9, v15, v13, vcc
	v_pk_fma_f32 v[12:13], v[76:77], s[4:5], v[152:153] op_sel_hi:[1,0,1] neg_lo:[1,0,0] neg_hi:[1,0,0]
	v_pk_fma_f32 v[14:15], v[72:73], s[4:5], v[154:155] op_sel_hi:[1,0,1] neg_lo:[1,0,0] neg_hi:[1,0,0]
	v_exp_f32_e32 v12, v12
	v_exp_f32_e32 v13, v13
	v_exp_f32_e32 v14, v14
	v_exp_f32_e32 v15, v15
	v_sqrt_f32_e32 v9, v9
	v_pk_add_f32 v[12:13], v[12:13], 1.0 op_sel_hi:[1,0]
	v_mov_b64_e32 v[24:25], v[56:57]
	v_rcp_f32_e32 v12, v12
	v_rcp_f32_e32 v13, v13
	v_pk_add_f32 v[14:15], v[14:15], 1.0 op_sel_hi:[1,0]
	v_pk_mul_f32 v[88:89], v[10:11], v[8:9]
	v_rcp_f32_e32 v14, v14
	v_pk_mul_f32 v[12:13], v[156:157], v[12:13]
	v_rcp_f32_e32 v15, v15
	v_exp_f32_e32 v72, v12
	v_exp_f32_e32 v73, v13
	v_pk_mul_f32 v[12:13], v[12:13], s[6:7] op_sel_hi:[1,0]
	v_pk_mul_f32 v[8:9], v[160:161], v[14:15]
	v_pk_fma_f32 v[6:7], v[12:13], s[0:1], v[6:7] op_sel_hi:[1,0,0]
	v_pk_fma_f32 v[16:17], v[72:73], v[72:73], 1.0 op_sel_hi:[1,1,0] neg_lo:[1,0,0] neg_hi:[1,0,0]
	v_pk_fma_f32 v[6:7], v[12:13], v[6:7], s[8:9] op_sel_hi:[1,1,0]
	v_cmp_lt_f32_e32 vcc, s7, v12
	v_pk_fma_f32 v[6:7], v[12:13], v[6:7], 0.5 op_sel_hi:[1,1,0]
	v_mov_b32_e32 v74, v89
	v_pk_fma_f32 v[6:7], v[12:13], v[6:7], 1.0 op_sel_hi:[1,1,0]
	v_readlane_b32 s0, v244, 52
	v_pk_mul_f32 v[6:7], v[12:13], v[6:7] neg_lo:[0,1] neg_hi:[0,1]
	v_readlane_b32 s1, v244, 53
	v_cndmask_b32_e32 v6, v16, v6, vcc
	v_cmp_lt_f32_e32 vcc, s7, v13
	v_sqrt_f32_e32 v6, v6
	v_mov_b64_e32 v[36:37], v[64:65]
	v_cndmask_b32_e32 v7, v17, v7, vcc
	v_sqrt_f32_e32 v7, v7
	v_mov_b32_e32 v239, v102
	v_mov_b32_e32 v240, v103
	v_mov_b32_e32 v241, v172
	v_pk_mul_f32 v[90:91], v[8:9], v[6:7]
	v_cvt_pk_bf16_f32 v6, v102, v103
	v_cvt_pk_bf16_f32 v7, v172, v78
	v_cvt_pk_bf16_f32 v8, v79, v99
	v_cvt_pk_bf16_f32 v9, v174, v94
	v_mov_b32_e32 v242, v78
	s_nop 1
v_fmac_f32_dpp v88, v216, v70 row_shl:15 row_mask:0xf bank_mask:0xf
 v_fmac_f32_dpp v74, v217, v71 row_shl:15 row_mask:0xf bank_mask:0xf
v_fmac_f32_dpp v90, v218, v72 row_shl:15 row_mask:0xf bank_mask:0xf
 v_fmac_f32_dpp v91, v219, v73 row_shl:15 row_mask:0xf bank_mask:0xf
v_mul_f32_dpp v70, v171, v70 row_shl:15 row_mask:0xf bank_mask:0xf
 v_mul_f32_dpp v71, v213, v71 row_shl:15 row_mask:0xf bank_mask:0xf
v_mul_f32_dpp v72, v214, v72 row_shl:15 row_mask:0xf bank_mask:0xf
 v_mul_f32_dpp v73, v215, v73 row_shl:15 row_mask:0xf bank_mask:0xf
v_fmac_f32_dpp v88, v88, v70 row_shr:1 row_mask:0xf bank_mask:0xf
 v_fmac_f32_dpp v74, v74, v71 row_shr:1 row_mask:0xf bank_mask:0xf
v_fmac_f32_dpp v90, v90, v72 row_shr:1 row_mask:0xf bank_mask:0xf
 v_fmac_f32_dpp v91, v91, v73 row_shr:1 row_mask:0xf bank_mask:0xf
v_mul_f32_dpp v70, v70, v70 row_shr:1 row_mask:0xf bank_mask:0xf
 v_mul_f32_dpp v71, v71, v71 row_shr:1 row_mask:0xf bank_mask:0xf
v_mul_f32_dpp v72, v72, v72 row_shr:1 row_mask:0xf bank_mask:0xf
 v_mul_f32_dpp v73, v73, v73 row_shr:1 row_mask:0xf bank_mask:0xf
v_fmac_f32_dpp v88, v88, v70 row_shr:2 row_mask:0xf bank_mask:0xf
 v_fmac_f32_dpp v74, v74, v71 row_shr:2 row_mask:0xf bank_mask:0xf
v_fmac_f32_dpp v90, v90, v72 row_shr:2 row_mask:0xf bank_mask:0xf
 v_fmac_f32_dpp v91, v91, v73 row_shr:2 row_mask:0xf bank_mask:0xf
v_mul_f32_dpp v70, v70, v70 row_shr:2 row_mask:0xf bank_mask:0xf
 v_mul_f32_dpp v71, v71, v71 row_shr:2 row_mask:0xf bank_mask:0xf
v_mul_f32_dpp v72, v72, v72 row_shr:2 row_mask:0xf bank_mask:0xf
 v_mul_f32_dpp v73, v73, v73 row_shr:2 row_mask:0xf bank_mask:0xf
v_fmac_f32_dpp v88, v88, v70 row_shr:4 row_mask:0xf bank_mask:0xf
 v_fmac_f32_dpp v74, v74, v71 row_shr:4 row_mask:0xf bank_mask:0xf
v_fmac_f32_dpp v90, v90, v72 row_shr:4 row_mask:0xf bank_mask:0xf
 v_fmac_f32_dpp v91, v91, v73 row_shr:4 row_mask:0xf bank_mask:0xf
v_mul_f32_dpp v70, v70, v70 row_shr:4 row_mask:0xf bank_mask:0xf
 v_mul_f32_dpp v71, v71, v71 row_shr:4 row_mask:0xf bank_mask:0xf
v_mul_f32_dpp v72, v72, v72 row_shr:4 row_mask:0xf bank_mask:0xf
 v_mul_f32_dpp v73, v73, v73 row_shr:4 row_mask:0xf bank_mask:0xf
v_fmac_f32_dpp v88, v88, v70 row_shr:8 row_mask:0xf bank_mask:0xf
 v_fmac_f32_dpp v74, v74, v71 row_shr:8 row_mask:0xf bank_mask:0xf
v_fmac_f32_dpp v90, v90, v72 row_shr:8 row_mask:0xf bank_mask:0xf
 v_fmac_f32_dpp v91, v91, v73 row_shr:8 row_mask:0xf bank_mask:0xf
v_mul_f32_dpp v70, v70, v70 row_shr:8 row_mask:0xf bank_mask:0xf
 v_mul_f32_dpp v71, v71, v71 row_shr:8 row_mask:0xf bank_mask:0xf
v_mul_f32_dpp v72, v72, v72 row_shr:8 row_mask:0xf bank_mask:0xf
 v_mul_f32_dpp v73, v73, v73 row_shr:8 row_mask:0xf bank_mask:0xf
s_nop 1

	v_ashrrev_i32_e32 v171, 31, v170
	v_lshlrev_b64 v[10:11], 10, v[170:171]
	v_lshl_add_u64 v[12:13], s[0:1], 0, v[10:11]
	v_readlane_b32 s0, v244, 54
	v_lshl_add_u64 v[14:15], v[12:13], 0, v[166:167]
	v_readlane_b32 s1, v244, 55
	global_store_dwordx4 v[14:15], v[6:9], off
	v_lshl_add_u64 v[12:13], v[12:13], 0, v[164:165]
	v_lshl_add_u64 v[10:11], s[0:1], 0, v[10:11]
	v_cvt_pk_bf16_f32 v6, v84, v85
	v_cvt_pk_bf16_f32 v7, v86, v87
	v_cvt_pk_bf16_f32 v8, v88, v74
	v_cvt_pk_bf16_f32 v9, v90, v91
	global_store_dwordx4 v[12:13], v[6:9], off
	v_lshl_add_u64 v[12:13], v[10:11], 0, v[166:167]
	v_lshl_add_u64 v[10:11], v[10:11], 0, v[164:165]
	v_cvt_pk_bf16_f32 v6, v100, v4
	v_cvt_pk_bf16_f32 v7, v5, v97
	v_cvt_pk_bf16_f32 v8, v92, v96
	v_cvt_pk_bf16_f32 v9, v178, v98
	global_store_dwordx4 v[12:13], v[6:9], off
	v_mov_b64_e32 v[14:15], v[38:39]
	v_mov_b32_e32 v171, v70
	v_cvt_pk_bf16_f32 v6, v80, v81
	v_cvt_pk_bf16_f32 v7, v82, v83
	v_cvt_pk_bf16_f32 v8, v70, v71
	v_cvt_pk_bf16_f32 v9, v72, v73
	global_store_dwordx4 v[10:11], v[6:9], off
	v_mov_b64_e32 v[10:11], v[42:43]
	v_mov_b32_e32 v213, v71
	v_mov_b64_e32 v[6:7], v[50:51]
	v_mov_b32_e32 v214, v72
	v_mov_b32_e32 v215, v73
	v_mov_b64_e32 v[12:13], v[44:45]
	v_mov_b64_e32 v[8:9], v[52:53]
	v_mov_b64_e32 v[16:17], v[40:41]
	v_mov_b32_e32 v232, v79
	v_mov_b32_e32 v233, v99
	v_mov_b32_e32 v234, v174
	v_mov_b32_e32 v235, v94
	v_mov_b32_e32 v224, v84
	v_mov_b32_e32 v225, v85
	v_mov_b32_e32 v226, v86
	v_mov_b32_e32 v227, v87
	v_mov_b32_e32 v216, v88
	v_mov_b32_e32 v217, v74
	v_mov_b32_e32 v218, v90
	v_mov_b32_e32 v219, v91
	s_cbranch_scc1 .LBB0_227
